# v29 + XCD leader's early invalidate moved from right after the L2 write-back to just after the cross-XCD arrival atomic is issued (overlaps the atomic round trip)
# baseline (speedup 1.0000x reference)
.LBB0_42:
	s_or_b64 exec, exec, s[10:11]
	buffer_inv sc1
	v_cvt_f32_u32_e32 v4, v1
	s_waitcnt vmcnt(0)
	v_readfirstlane_b32 s9, v3
	v_sub_u32_e32 v3, 0, v1
	s_add_u32 s8, s92, 0x3500
	v_rcp_iflag_f32_e32 v4, v4
	v_add_u32_e32 v2, s9, v2
	v_add_u32_e32 v5, 1, v2
	s_addc_u32 s9, s93, 0
	v_mul_f32_e32 v4, 0x4f7ffffe, v4
	v_cvt_u32_f32_e32 v4, v4
	s_mov_b64 s[12:13], -1
	v_mul_lo_u32 v3, v3, v4
	v_mul_hi_u32 v3, v4, v3
	v_add_u32_e32 v3, v4, v3
	v_mul_hi_u32 v3, v2, v3
	v_mul_lo_u32 v4, v3, v1
	v_sub_u32_e32 v2, v2, v4
	v_add_u32_e32 v6, 1, v3
	v_sub_u32_e32 v4, v2, v1
	v_cmp_ge_u32_e32 vcc, v2, v1
	s_nop 1
	v_cndmask_b32_e32 v3, v3, v6, vcc
	v_cndmask_b32_e32 v2, v2, v4, vcc
	v_add_u32_e32 v4, 1, v3
	v_cmp_ge_u32_e32 vcc, v2, v1
	s_nop 1
	v_cndmask_b32_e32 v4, v3, v4, vcc
	v_mul_lo_u32 v2, v1, v4
	v_add_u32_e32 v1, v2, v1
	v_cmp_ne_u32_e32 vcc, v5, v1
	v_mov_b64_e32 v[2:3], s[8:9]
	s_and_saveexec_b64 s[10:11], vcc
	s_cbranch_execz .Lpush_0
	v_mov_b32_e32 v1, 0
	global_load_dword v2, v1, s[8:9] sc1
	s_mov_b64 s[16:17], 0
	s_waitcnt vmcnt(0)
	v_cmp_eq_u32_e32 vcc, v2, v4
	s_and_saveexec_b64 s[14:15], vcc
	s_cbranch_execz .LBB0_53
	s_add_u32 s12, s92, 0x200
	s_addc_u32 s13, s93, 0
	s_mov_b32 s26, 1
	s_branch .LBB0_46

.LBB0_184:
	s_or_b64 exec, exec, s[8:9]
	buffer_inv sc1
	v_cvt_f32_u32_e32 v4, v1
	s_waitcnt vmcnt(0)
	v_readfirstlane_b32 s7, v3
	v_sub_u32_e32 v3, 0, v1
	s_add_u32 s6, s92, 0x3500
	v_rcp_iflag_f32_e32 v4, v4
	v_add_u32_e32 v2, s7, v2
	v_add_u32_e32 v5, 1, v2
	s_addc_u32 s7, s93, 0
	v_mul_f32_e32 v4, 0x4f7ffffe, v4
	v_cvt_u32_f32_e32 v4, v4
	s_mov_b64 s[10:11], -1
	v_mul_lo_u32 v3, v3, v4
	v_mul_hi_u32 v3, v4, v3
	v_add_u32_e32 v3, v4, v3
	v_mul_hi_u32 v3, v2, v3
	v_mul_lo_u32 v4, v3, v1
	v_sub_u32_e32 v2, v2, v4
	v_add_u32_e32 v6, 1, v3
	v_sub_u32_e32 v4, v2, v1
	v_cmp_ge_u32_e32 vcc, v2, v1
	s_nop 1
	v_cndmask_b32_e32 v3, v3, v6, vcc
	v_cndmask_b32_e32 v2, v2, v4, vcc
	v_add_u32_e32 v4, 1, v3
	v_cmp_ge_u32_e32 vcc, v2, v1
	s_nop 1
	v_cndmask_b32_e32 v4, v3, v4, vcc
	v_mul_lo_u32 v2, v1, v4
	v_add_u32_e32 v1, v2, v1
	v_cmp_ne_u32_e32 vcc, v5, v1
	v_mov_b64_e32 v[2:3], s[6:7]
	s_and_saveexec_b64 s[8:9], vcc
	s_cbranch_execz .Lpush_1
	v_mov_b32_e32 v1, 0
	global_load_dword v2, v1, s[6:7] sc1
	s_mov_b64 s[14:15], 0
	s_waitcnt vmcnt(0)
	v_cmp_eq_u32_e32 vcc, v2, v4
	s_and_saveexec_b64 s[12:13], vcc
	s_cbranch_execz .LBB0_195
	s_add_u32 s10, s92, 0x200
	s_addc_u32 s11, s93, 0
	s_mov_b32 s24, 1
	s_branch .LBB0_188

.LBB0_247:
	s_or_b64 exec, exec, s[6:7]
	buffer_inv sc1
	v_cvt_f32_u32_e32 v4, v1
	s_waitcnt vmcnt(0)
	v_readfirstlane_b32 s5, v3
	v_sub_u32_e32 v3, 0, v1
	s_add_u32 s4, s92, 0x3500
	v_rcp_iflag_f32_e32 v4, v4
	v_add_u32_e32 v2, s5, v2
	v_add_u32_e32 v5, 1, v2
	s_addc_u32 s5, s93, 0
	v_mul_f32_e32 v4, 0x4f7ffffe, v4
	v_cvt_u32_f32_e32 v4, v4
	s_mov_b64 s[8:9], -1
	v_mul_lo_u32 v3, v3, v4
	v_mul_hi_u32 v3, v4, v3
	v_add_u32_e32 v3, v4, v3
	v_mul_hi_u32 v3, v2, v3
	v_mul_lo_u32 v4, v3, v1
	v_sub_u32_e32 v2, v2, v4
	v_add_u32_e32 v6, 1, v3
	v_sub_u32_e32 v4, v2, v1
	v_cmp_ge_u32_e32 vcc, v2, v1
	s_nop 1
	v_cndmask_b32_e32 v3, v3, v6, vcc
	v_cndmask_b32_e32 v2, v2, v4, vcc
	v_add_u32_e32 v4, 1, v3
	v_cmp_ge_u32_e32 vcc, v2, v1
	s_nop 1
	v_cndmask_b32_e32 v4, v3, v4, vcc
	v_mul_lo_u32 v2, v1, v4
	v_add_u32_e32 v1, v2, v1
	v_cmp_ne_u32_e32 vcc, v5, v1
	v_mov_b64_e32 v[2:3], s[4:5]
	s_and_saveexec_b64 s[6:7], vcc
	s_cbranch_execz .Lpush_2
	v_mov_b32_e32 v1, 0
	global_load_dword v2, v1, s[4:5] sc1
	s_mov_b64 s[12:13], 0
	s_waitcnt vmcnt(0)
	v_cmp_eq_u32_e32 vcc, v2, v4
	s_and_saveexec_b64 s[10:11], vcc
	s_cbranch_execz .LBB0_258
	s_add_u32 s8, s92, 0x200
	s_addc_u32 s9, s93, 0
	s_mov_b32 s22, 1
	s_branch .LBB0_251

.LBB0_429:
	s_or_b64 exec, exec, s[8:9]
	buffer_inv sc1
	s_waitcnt vmcnt(0)
	v_readfirstlane_b32 s6, v3
	v_sub_u32_e32 v4, 0, v2
	s_mov_b64 s[10:11], -1
	v_add_u32_e32 v3, s6, v1
	v_cvt_f32_u32_e32 v1, v2
	s_add_u32 s6, s92, 0x3500
	s_addc_u32 s7, s93, 0
	v_rcp_iflag_f32_e32 v1, v1
	s_nop 0
	v_mul_f32_e32 v1, 0x4f7ffffe, v1
	v_cvt_u32_f32_e32 v1, v1
	v_mul_lo_u32 v4, v4, v1
	v_mul_hi_u32 v4, v1, v4
	v_add_u32_e32 v1, v1, v4
	v_mul_hi_u32 v1, v3, v1
	v_mul_lo_u32 v4, v1, v2
	v_sub_u32_e32 v4, v3, v4
	v_cmp_ge_u32_e32 vcc, v4, v2
	v_add_u32_e32 v5, 1, v1
	v_add_u32_e32 v3, 1, v3
	v_cndmask_b32_e32 v1, v1, v5, vcc
	v_sub_u32_e32 v5, v4, v2
	v_cndmask_b32_e32 v4, v4, v5, vcc
	v_cmp_ge_u32_e32 vcc, v4, v2
	v_add_u32_e32 v4, 1, v1
	s_nop 0
	v_cndmask_b32_e32 v1, v1, v4, vcc
	v_mul_lo_u32 v4, v2, v1
	v_add_u32_e32 v2, v4, v2
	v_cmp_ne_u32_e32 vcc, v3, v2
	v_mov_b64_e32 v[2:3], s[6:7]
	s_and_saveexec_b64 s[8:9], vcc
	s_cbranch_execz .Lpush_3
	v_mov_b32_e32 v2, 0
	global_load_dword v3, v2, s[6:7] sc1
	s_mov_b64 s[14:15], 0
	s_waitcnt vmcnt(0)
	v_cmp_eq_u32_e32 vcc, v3, v1
	s_and_saveexec_b64 s[12:13], vcc
	s_cbranch_execz .LBB0_440
	s_add_u32 s10, s92, 0x200
	s_addc_u32 s11, s93, 0
	s_mov_b32 s24, 1
	s_branch .LBB0_433

.LBB0_493:
	s_or_b64 exec, exec, s[8:9]
	buffer_inv sc1
	v_cvt_f32_u32_e32 v4, v1
	s_waitcnt vmcnt(0)
	v_readfirstlane_b32 s6, v3
	s_add_u32 s8, s92, 0x3500
	s_addc_u32 s9, s93, 0
	v_rcp_iflag_f32_e32 v4, v4
	v_add_u32_e32 v2, s6, v2
	v_add_u32_e32 v5, 1, v2
	s_mov_b64 s[10:11], -1
	v_mul_f32_e32 v3, 0x4f7ffffe, v4
	v_cvt_u32_f32_e32 v3, v3
	v_sub_u32_e32 v4, 0, v1
	v_mul_lo_u32 v4, v4, v3
	v_mul_hi_u32 v4, v3, v4
	v_add_u32_e32 v3, v3, v4
	v_mul_hi_u32 v3, v2, v3
	v_mul_lo_u32 v4, v3, v1
	v_sub_u32_e32 v2, v2, v4
	v_add_u32_e32 v6, 1, v3
	v_cmp_ge_u32_e32 vcc, v2, v1
	v_sub_u32_e32 v4, v2, v1
	s_nop 0
	v_cndmask_b32_e32 v3, v3, v6, vcc
	v_cndmask_b32_e32 v2, v2, v4, vcc
	v_add_u32_e32 v4, 1, v3
	v_cmp_ge_u32_e32 vcc, v2, v1
	s_nop 1
	v_cndmask_b32_e32 v4, v3, v4, vcc
	v_mul_lo_u32 v2, v1, v4
	v_add_u32_e32 v1, v2, v1
	v_cmp_ne_u32_e32 vcc, v5, v1
	v_mov_b64_e32 v[2:3], s[8:9]
	s_and_saveexec_b64 s[6:7], vcc
	s_cbranch_execz .Lpush_4
	v_mov_b32_e32 v1, 0
	global_load_dword v2, v1, s[8:9] sc1
	s_mov_b64 s[14:15], 0
	s_waitcnt vmcnt(0)
	v_cmp_eq_u32_e32 vcc, v2, v4
	s_and_saveexec_b64 s[12:13], vcc
	s_cbranch_execz .LBB0_504
	s_add_u32 s10, s92, 0x200
	s_addc_u32 s11, s93, 0
	s_mov_b32 s24, 1
	s_branch .LBB0_497

.LBB0_617:
	s_or_b64 exec, exec, s[6:7]
	buffer_inv sc1
	v_cvt_f32_u32_e32 v4, v1
	s_waitcnt vmcnt(0)
	v_readfirstlane_b32 s4, v3
	s_add_u32 s6, s92, 0x3500
	s_addc_u32 s7, s93, 0
	v_rcp_iflag_f32_e32 v4, v4
	v_add_u32_e32 v2, s4, v2
	v_add_u32_e32 v5, 1, v2
	s_mov_b64 s[8:9], -1
	v_mul_f32_e32 v3, 0x4f7ffffe, v4
	v_cvt_u32_f32_e32 v3, v3
	v_sub_u32_e32 v4, 0, v1
	v_mul_lo_u32 v4, v4, v3
	v_mul_hi_u32 v4, v3, v4
	v_add_u32_e32 v3, v3, v4
	v_mul_hi_u32 v3, v2, v3
	v_mul_lo_u32 v4, v3, v1
	v_sub_u32_e32 v2, v2, v4
	v_add_u32_e32 v6, 1, v3
	v_cmp_ge_u32_e32 vcc, v2, v1
	v_sub_u32_e32 v4, v2, v1
	s_nop 0
	v_cndmask_b32_e32 v3, v3, v6, vcc
	v_cndmask_b32_e32 v2, v2, v4, vcc
	v_add_u32_e32 v4, 1, v3
	v_cmp_ge_u32_e32 vcc, v2, v1
	s_nop 1
	v_cndmask_b32_e32 v4, v3, v4, vcc
	v_mul_lo_u32 v2, v1, v4
	v_add_u32_e32 v1, v2, v1
	v_cmp_ne_u32_e32 vcc, v5, v1
	v_mov_b64_e32 v[2:3], s[6:7]
	s_and_saveexec_b64 s[4:5], vcc
	s_cbranch_execz .Lpush_5
	v_mov_b32_e32 v1, 0
	global_load_dword v2, v1, s[6:7] sc1
	s_mov_b64 s[12:13], 0
	s_waitcnt vmcnt(0)
	v_cmp_eq_u32_e32 vcc, v2, v4
	s_and_saveexec_b64 s[10:11], vcc
	s_cbranch_execz .LBB0_628
	s_add_u32 s8, s92, 0x200
	s_addc_u32 s9, s93, 0
	s_mov_b32 s24, 1
	s_branch .LBB0_621

.LBB0_877:
	s_or_b64 exec, exec, s[6:7]
	buffer_inv sc1
	v_cvt_f32_u32_e32 v4, v1
	s_waitcnt vmcnt(0)
	v_readfirstlane_b32 s4, v3
	s_add_u32 s6, s92, 0x3500
	s_addc_u32 s7, s93, 0
	v_rcp_iflag_f32_e32 v4, v4
	v_add_u32_e32 v2, s4, v2
	v_add_u32_e32 v5, 1, v2
	s_mov_b64 s[8:9], -1
	v_mul_f32_e32 v3, 0x4f7ffffe, v4
	v_cvt_u32_f32_e32 v3, v3
	v_sub_u32_e32 v4, 0, v1
	v_mul_lo_u32 v4, v4, v3
	v_mul_hi_u32 v4, v3, v4
	v_add_u32_e32 v3, v3, v4
	v_mul_hi_u32 v3, v2, v3
	v_mul_lo_u32 v4, v3, v1
	v_sub_u32_e32 v2, v2, v4
	v_add_u32_e32 v6, 1, v3
	v_cmp_ge_u32_e32 vcc, v2, v1
	v_sub_u32_e32 v4, v2, v1
	s_nop 0
	v_cndmask_b32_e32 v3, v3, v6, vcc
	v_cndmask_b32_e32 v2, v2, v4, vcc
	v_add_u32_e32 v4, 1, v3
	v_cmp_ge_u32_e32 vcc, v2, v1
	s_nop 1
	v_cndmask_b32_e32 v4, v3, v4, vcc
	v_mul_lo_u32 v2, v1, v4
	v_add_u32_e32 v1, v2, v1
	v_cmp_ne_u32_e32 vcc, v5, v1
	v_mov_b64_e32 v[2:3], s[6:7]
	s_and_saveexec_b64 s[4:5], vcc
	s_cbranch_execz .Lpush_8
	v_mov_b32_e32 v1, 0
	global_load_dword v2, v1, s[6:7] sc1
	s_mov_b64 s[12:13], 0
	s_waitcnt vmcnt(0)
	v_cmp_eq_u32_e32 vcc, v2, v4
	s_and_saveexec_b64 s[10:11], vcc
	s_cbranch_execz .LBB0_888
	s_add_u32 s8, s92, 0x200
	s_addc_u32 s9, s93, 0
	s_mov_b32 s22, 1
	s_branch .LBB0_881

.LBB0_936:
	s_or_b64 exec, exec, s[8:9]
	buffer_inv sc1
	v_cvt_f32_u32_e32 v4, v1
	s_waitcnt vmcnt(0)
	v_readfirstlane_b32 s4, v3
	s_add_u32 s8, s92, 0x3500
	s_addc_u32 s9, s93, 0
	v_rcp_iflag_f32_e32 v4, v4
	v_add_u32_e32 v2, s4, v2
	v_add_u32_e32 v5, 1, v2
	s_mov_b64 s[10:11], -1
	v_mul_f32_e32 v3, 0x4f7ffffe, v4
	v_cvt_u32_f32_e32 v3, v3
	v_sub_u32_e32 v4, 0, v1
	v_mul_lo_u32 v4, v4, v3
	v_mul_hi_u32 v4, v3, v4
	v_add_u32_e32 v3, v3, v4
	v_mul_hi_u32 v3, v2, v3
	v_mul_lo_u32 v4, v3, v1
	v_sub_u32_e32 v2, v2, v4
	v_add_u32_e32 v6, 1, v3
	v_cmp_ge_u32_e32 vcc, v2, v1
	v_sub_u32_e32 v4, v2, v1
	s_nop 0
	v_cndmask_b32_e32 v3, v3, v6, vcc
	v_cndmask_b32_e32 v2, v2, v4, vcc
	v_add_u32_e32 v4, 1, v3
	v_cmp_ge_u32_e32 vcc, v2, v1
	s_nop 1
	v_cndmask_b32_e32 v4, v3, v4, vcc
	v_mul_lo_u32 v2, v1, v4
	v_add_u32_e32 v1, v2, v1
	v_cmp_ne_u32_e32 vcc, v5, v1
	v_mov_b64_e32 v[2:3], s[8:9]
	s_and_saveexec_b64 s[4:5], vcc
	s_cbranch_execz .Lpush_9
	v_mov_b32_e32 v1, 0
	global_load_dword v2, v1, s[8:9] sc1
	s_mov_b64 s[14:15], 0
	s_waitcnt vmcnt(0)
	v_cmp_eq_u32_e32 vcc, v2, v4
	s_and_saveexec_b64 s[12:13], vcc
	s_cbranch_execz .LBB0_947
	s_add_u32 s10, s92, 0x200
	s_addc_u32 s11, s93, 0
	s_mov_b32 s24, 1
	s_branch .LBB0_940
